# forgetting attention: separate tile body for key tiles away from the causal diagonal (per-element diagonal compare/mask/select removed there, 64 selects per tile)
# speedup vs baseline: 1.0099x; 1.0099x over previous
; #define AT_STAGE(tile) do { const int _i = (tile) < nkt ? (tile) : (nkt - 1); const int _t = AT_TILE(_i); char* _s = dynsmem + ((tile) & 3) * 32768 + tid * 16; \
;     const u16* _kg = Kg0 + (size_t)_t * 64 * ldk; const u16* _vg = Vg0 + _t * 64; \
;     AT_GLDS(_kg, _s); AT_GLDS(_kg + k32, _s + 8192); AT_GLDS(_vg, _s + 16384); AT_GLDS(_vg + v64, _s + 16384 + 8192); } while (0)
; template <int MODE>
; DI void attn_item(const u16* Qp, int ldq, const u16* Kp, int ldk, const u16* VTp, int ldv, u16* Op, int ldo,
;                   int q0, int nkt, const float* Fc, const unsigned* BM, float kmaxn, char* smem) {
;     ...
;   for (int kt = 0; kt < nkt; ++kt) {
;     const char* sKn = smem + ((kt + 1) & 3) * 32768;
;     const char* sV = smem + (kt & 3) * 32768 + 16384;
;     const float* sF = fct + (kt & 3) * 64;
;     const int ts = AT_TILE(kt) * 64;
;     const bool more1 = (kt + 1 < nkt);
;     uint2 bwn = make_uint2(0xffffffffu, 0xffffffffu);
;     const int tn = AT_TILE(more1 ? (kt + 1) : kt);
;     float flast = 0.f;
;     if (MODE == 1) { rf = *(const f32x4*)(Fc + tn * 64 + (tid & 15) * 4); flast = Fc[tn * 64 + 63]; }
;     if (MODE == 2) bwn = *(const uint2*)(bmq + tn * 2);
;     AT_STAGE(kt + 3);
;     const bool diag = (MODE == 1) && (ts + 63 > qw);
;     float mx = -1e30f;
;     if (MODE == 1) {
; #pragma unroll
;       for (int k2 = 0; k2 < 2; ++k2)
; #pragma unroll
;         for (int j = 0; j < 4; ++j) {
;           const int kl = 32 * k2 + 16 * (j >> 1) + 8 * h + 4 * (j & 1);
;           const f32x4 f4 = *(const f32x4*)(sF + kl);
; #pragma unroll
;           for (int i = 0; i < 4; ++i) {
;             float x = sc[k2][j * 4 + i] * c1 + (fcq - f4[i]);
;             if (diag && (ts + kl + i > q)) x = -1e30f;
;             sc[k2][j * 4 + i] = x;
;             mx = fmaxf(mx, x);
;           }
;         }
.LBB0_475:
	s_add_i32 s18, s14, 1
	s_and_b32 s15, s14, 3
	s_cmp_lt_i32 s18, s63
	s_cselect_b32 s10, s18, s14
	s_sub_i32 s10, s51, s10
	s_lshl_b32 s10, s10, 6
	s_ashr_i32 s11, s10, 31
	s_lshl_b64 s[10:11], s[10:11], 2
	s_add_u32 s10, s38, s10
	s_addc_u32 s11, s39, s11
	global_load_dwordx4 v[130:133], v142, s[10:11]
	global_load_dword v165, v1, s[10:11] offset:252
	s_add_i32 s10, s14, 3
	s_min_i32 s10, s10, s51
	s_sub_i32 s14, s51, s10
	s_and_b32 s10, s17, 0x18000
	v_add_u32_e32 v170, s10, v144
	v_mad_i64_i32 v[166:167], s[10:11], s14, v211, v[136:137]
	s_lshl_b32 s10, s14, 6
	s_ashr_i32 s11, s10, 31
	v_lshl_add_u64 v[168:169], s[10:11], 1, v[138:139]
	v_readfirstlane_b32 s10, v170
	v_add_u32_e32 v171, 0x2000, v170
	s_mov_b32 m0, s10
	v_readfirstlane_b32 s10, v171
	global_load_lds_dwordx4 v[166:167], off
	v_lshl_add_u64 v[166:167], v[166:167], 0, s[84:85]
	s_mov_b32 m0, s10
	v_add_u32_e32 v171, s16, v0
	global_load_lds_dwordx4 v[166:167], off
	v_add_u32_e32 v166, 0x4000, v170
	v_subrev_u32_e32 v176, 63, v171
	v_readfirstlane_b32 s10, v166
	s_mov_b32 m0, s10
	v_lshl_add_u64 v[166:167], v[168:169], 0, s[86:87]
	global_load_lds_dwordx4 v[168:169], off
	v_add_u32_e32 v168, 0x6000, v170
	v_lshl_add_u32 v170, s15, 8, v162
	v_readfirstlane_b32 s10, v168
	s_mov_b32 m0, s10
	v_cmp_gt_i32_e64 s[10:11], s16, v140
	global_load_lds_dwordx4 v[166:167], off
	ds_read_b128 v[166:169], v170
	ds_read_b128 v[172:175], v170 offset:16
	ds_read_b128 v[212:215], v170 offset:64
	ds_read_b128 v[234:237], v170 offset:80
	ds_read_b128 v[238:241], v170 offset:128
	ds_read_b128 v[242:245], v170 offset:144
	ds_read_b128 v[246:249], v170 offset:192
	ds_read_b128 v[250:253], v170 offset:208
	s_cmp_eq_u64 s[10:11], 0
	s_cbranch_scc1 .Lfox_fast
	v_cmp_gt_i32_e32 vcc, v176, v134
	s_and_b64 vcc, s[10:11], vcc
	s_mov_b32 s14, 0xf149f2ca
	s_waitcnt lgkmcnt(0)
	v_sub_f32_e32 v166, v141, v166
	v_fmac_f32_e32 v166, 0x3e0293ee, v66
	v_sub_f32_e32 v66, v141, v167
	v_cndmask_b32_e32 v185, v166, v219, vcc
	v_fmac_f32_e32 v66, 0x3e0293ee, v67
	v_cmp_ge_i32_e32 vcc, v176, v134
	v_sub_f32_e32 v67, v141, v168
	s_and_b64 vcc, s[10:11], vcc
	v_fmac_f32_e32 v67, 0x3e0293ee, v68
	v_subrev_u32_e32 v68, 61, v171
	v_cndmask_b32_e32 v191, v66, v219, vcc
	v_cmp_gt_i32_e32 vcc, v68, v134
	s_and_b64 vcc, s[10:11], vcc
	v_subrev_u32_e32 v68, 60, v171
	v_cndmask_b32_e32 v192, v67, v219, vcc
	v_sub_f32_e32 v67, v141, v169
	v_cmp_gt_i32_e32 vcc, v68, v134
	v_fmac_f32_e32 v67, 0x3e0293ee, v69
	s_and_b64 vcc, s[10:11], vcc
	v_cndmask_b32_e32 v193, v67, v219, vcc
	v_subrev_u32_e32 v67, 59, v171
	v_sub_f32_e32 v68, v141, v172
	v_cmp_gt_i32_e32 vcc, v67, v134
	v_fmac_f32_e32 v68, 0x3e0293ee, v70
	s_and_b64 vcc, s[10:11], vcc
	v_cndmask_b32_e32 v198, v68, v219, vcc
	v_sub_f32_e32 v68, v141, v173
	v_cmp_ge_i32_e32 vcc, v67, v134
	v_fmac_f32_e32 v68, 0x3e0293ee, v71
	s_and_b64 vcc, s[10:11], vcc
	v_cndmask_b32_e32 v197, v68, v219, vcc
	v_subrev_u32_e32 v68, 57, v171
	v_sub_f32_e32 v67, v141, v174
	v_cmp_gt_i32_e32 vcc, v68, v134
	v_fmac_f32_e32 v67, 0x3e0293ee, v72
	s_and_b64 vcc, s[10:11], vcc
	v_subrev_u32_e32 v68, 56, v171
	v_max3_f32 v66, v185, s14, v191
	v_cndmask_b32_e32 v195, v67, v219, vcc
	v_sub_f32_e32 v67, v141, v175
	v_cmp_gt_i32_e32 vcc, v68, v134
	v_max3_f32 v66, v66, v192, v193
	v_fmac_f32_e32 v67, 0x3e0293ee, v73
	s_and_b64 vcc, s[10:11], vcc
	v_max3_f32 v66, v66, v198, v197
	v_cndmask_b32_e32 v196, v67, v219, vcc
	v_max3_f32 v70, v66, v195, v196
	v_subrev_u32_e32 v71, 47, v171
	v_cmp_gt_i32_e32 vcc, v71, v134
	s_and_b64 vcc, s[10:11], vcc
	s_waitcnt lgkmcnt(0)
	v_sub_f32_e32 v66, v141, v212
	v_fmac_f32_e32 v66, 0x3e0293ee, v74
	v_cndmask_b32_e32 v184, v66, v219, vcc
	v_sub_f32_e32 v66, v141, v213
	v_cmp_ge_i32_e32 vcc, v71, v134
	v_fmac_f32_e32 v66, 0x3e0293ee, v75
	s_and_b64 vcc, s[10:11], vcc
	v_sub_f32_e32 v67, v141, v214
	v_subrev_u32_e32 v68, 45, v171
	v_cndmask_b32_e32 v183, v66, v219, vcc
	v_cmp_gt_i32_e32 vcc, v68, v134
	v_fmac_f32_e32 v67, 0x3e0293ee, v76
	s_and_b64 vcc, s[10:11], vcc
	v_subrev_u32_e32 v68, 44, v171
	v_cndmask_b32_e32 v182, v67, v219, vcc
	v_sub_f32_e32 v67, v141, v215
	v_cmp_gt_i32_e32 vcc, v68, v134
	v_fmac_f32_e32 v67, 0x3e0293ee, v77
	s_and_b64 vcc, s[10:11], vcc
	v_max3_f32 v66, v70, v184, v183
	v_cndmask_b32_e32 v179, v67, v219, vcc
	v_max3_f32 v70, v66, v182, v179
	v_subrev_u32_e32 v71, 43, v171
	v_cmp_gt_i32_e32 vcc, v71, v134
	s_and_b64 vcc, s[10:11], vcc
	s_waitcnt lgkmcnt(0)
	v_sub_f32_e32 v66, v141, v234
	v_fmac_f32_e32 v66, 0x3e0293ee, v78
	v_cndmask_b32_e32 v194, v66, v219, vcc
	v_sub_f32_e32 v66, v141, v235
	v_cmp_ge_i32_e32 vcc, v71, v134
	v_fmac_f32_e32 v66, 0x3e0293ee, v79
	s_and_b64 vcc, s[10:11], vcc
	v_sub_f32_e32 v67, v141, v236
	v_subrev_u32_e32 v68, 41, v171
	v_cndmask_b32_e32 v188, v66, v219, vcc
	v_cmp_gt_i32_e32 vcc, v68, v134
	v_fmac_f32_e32 v67, 0x3e0293ee, v80
	s_and_b64 vcc, s[10:11], vcc
	v_subrev_u32_e32 v68, 40, v171
	v_cndmask_b32_e32 v186, v67, v219, vcc
	v_sub_f32_e32 v67, v141, v237
	v_cmp_gt_i32_e32 vcc, v68, v134
	v_fmac_f32_e32 v67, 0x3e0293ee, v81
	s_and_b64 vcc, s[10:11], vcc
	v_max3_f32 v66, v70, v194, v188
	v_cndmask_b32_e32 v187, v67, v219, vcc
	v_max3_f32 v70, v66, v186, v187
	v_subrev_u32_e32 v71, 31, v171
	v_cmp_gt_i32_e32 vcc, v71, v134
	s_and_b64 vcc, s[10:11], vcc
	s_waitcnt lgkmcnt(0)
; DI float shflx(float v, int m, int lane) { return __int_as_float(__builtin_amdgcn_ds_bpermute((lane ^ m) << 2, __float_as_int(v))); }
; template <int MODE>
; DI void attn_item(const u16* Qp, int ldq, const u16* Kp, int ldk, const u16* VTp, int ldv, u16* Op, int ldo,
;                   int q0, int nkt, const float* Fc, const unsigned* BM, float kmaxn, char* smem) {
;     ...
;     if (MODE == 1) {
; #pragma unroll
;       for (int k2 = 0; k2 < 2; ++k2)
; #pragma unroll
;         for (int j = 0; j < 4; ++j) {
;           const int kl = 32 * k2 + 16 * (j >> 1) + 8 * h + 4 * (j & 1);
;           const f32x4 f4 = *(const f32x4*)(sF + kl);
; #pragma unroll
;           for (int i = 0; i < 4; ++i) {
;             float x = sc[k2][j * 4 + i] * c1 + (fcq - f4[i]);
;             if (diag && (ts + kl + i > q)) x = -1e30f;
;             sc[k2][j * 4 + i] = x;
;             mx = fmaxf(mx, x);
;           }
;         }
;     } else {
; #pragma unroll
;       for (int k2 = 0; k2 < 2; ++k2)
; #pragma unroll
;         for (int e = 0; e < 16; ++e) mx = fmaxf(mx, sc[k2][e]);
;       mx *= c1;
;     }
;     mx = fmaxf(mx, shflx(mx, 32, lane));
;     if (__any(mx > m_run + 8.f)) {
;       const float m_new = fmaxf(m_run, mx);
;       const float alpha = __builtin_amdgcn_exp2f(m_run - m_new);
;       m_run = m_new; l_run *= alpha;
; #pragma unroll
;       for (int i = 0; i < 4; ++i)
; #pragma unroll
;         for (int e = 0; e < 16; ++e) o[i][e] *= alpha;
;     }
	v_sub_f32_e32 v66, v141, v238
	v_fmac_f32_e32 v66, 0x3e0293ee, v82
	v_cndmask_b32_e32 v176, v66, v219, vcc
	v_sub_f32_e32 v66, v141, v239
	v_cmp_ge_i32_e32 vcc, v71, v134
	v_fmac_f32_e32 v66, 0x3e0293ee, v83
	s_and_b64 vcc, s[10:11], vcc
	v_sub_f32_e32 v67, v141, v240
	v_subrev_u32_e32 v68, 29, v171
	v_cndmask_b32_e32 v175, v66, v219, vcc
	v_cmp_gt_i32_e32 vcc, v68, v134
	v_fmac_f32_e32 v67, 0x3e0293ee, v84
	s_and_b64 vcc, s[10:11], vcc
	v_subrev_u32_e32 v68, 28, v171
	v_cndmask_b32_e32 v174, v67, v219, vcc
	v_sub_f32_e32 v67, v141, v241
	v_cmp_gt_i32_e32 vcc, v68, v134
	v_fmac_f32_e32 v67, 0x3e0293ee, v85
	s_and_b64 vcc, s[10:11], vcc
	v_max3_f32 v66, v70, v176, v175
	v_cndmask_b32_e32 v173, v67, v219, vcc
	v_max3_f32 v70, v66, v174, v173
	v_subrev_u32_e32 v71, 27, v171
	v_cmp_gt_i32_e32 vcc, v71, v134
	s_and_b64 vcc, s[10:11], vcc
	s_waitcnt lgkmcnt(0)
	v_sub_f32_e32 v66, v141, v242
	v_fmac_f32_e32 v66, 0x3e0293ee, v86
	v_cndmask_b32_e32 v190, v66, v219, vcc
	v_sub_f32_e32 v66, v141, v243
	v_cmp_ge_i32_e32 vcc, v71, v134
	v_fmac_f32_e32 v66, 0x3e0293ee, v87
	s_and_b64 vcc, s[10:11], vcc
	v_sub_f32_e32 v67, v141, v244
	v_subrev_u32_e32 v68, 25, v171
	v_cndmask_b32_e32 v180, v66, v219, vcc
	v_cmp_gt_i32_e32 vcc, v68, v134
	v_fmac_f32_e32 v67, 0x3e0293ee, v88
	s_and_b64 vcc, s[10:11], vcc
	v_subrev_u32_e32 v68, 24, v171
	v_cndmask_b32_e32 v177, v67, v219, vcc
	v_sub_f32_e32 v67, v141, v245
	v_cmp_gt_i32_e32 vcc, v68, v134
	v_fmac_f32_e32 v67, 0x3e0293ee, v89
	s_and_b64 vcc, s[10:11], vcc
	v_max3_f32 v66, v70, v190, v180
	v_cndmask_b32_e32 v178, v67, v219, vcc
	v_max3_f32 v70, v66, v177, v178
	v_add_u32_e32 v71, -15, v171
	v_cmp_gt_i32_e32 vcc, v71, v134
	s_and_b64 vcc, s[10:11], vcc
	s_waitcnt lgkmcnt(0)
	v_sub_f32_e32 v66, v141, v246
	v_fmac_f32_e32 v66, 0x3e0293ee, v90
	v_cndmask_b32_e32 v169, v66, v219, vcc
	v_sub_f32_e32 v66, v141, v247
	v_cmp_ge_i32_e32 vcc, v71, v134
	v_fmac_f32_e32 v66, 0x3e0293ee, v91
	s_and_b64 vcc, s[10:11], vcc
	v_sub_f32_e32 v67, v141, v248
	v_add_u32_e32 v68, -13, v171
	v_cndmask_b32_e32 v168, v66, v219, vcc
	v_cmp_gt_i32_e32 vcc, v68, v134
	v_fmac_f32_e32 v67, 0x3e0293ee, v92
	s_and_b64 vcc, s[10:11], vcc
	v_add_u32_e32 v68, -12, v171
	v_cndmask_b32_e32 v167, v67, v219, vcc
	v_sub_f32_e32 v67, v141, v249
	v_cmp_gt_i32_e32 vcc, v68, v134
	v_fmac_f32_e32 v67, 0x3e0293ee, v93
	s_and_b64 vcc, s[10:11], vcc
	v_max3_f32 v66, v70, v169, v168
	v_cndmask_b32_e32 v166, v67, v219, vcc
	v_max3_f32 v70, v66, v167, v166
	v_add_u32_e32 v71, -11, v171
	v_cmp_gt_i32_e32 vcc, v71, v134
	s_and_b64 vcc, s[10:11], vcc
	s_waitcnt lgkmcnt(0)
	v_sub_f32_e32 v66, v141, v250
	v_fmac_f32_e32 v66, 0x3e0293ee, v94
	v_cndmask_b32_e32 v181, v66, v219, vcc
	v_sub_f32_e32 v66, v141, v251
	v_cmp_ge_i32_e32 vcc, v71, v134
	v_fmac_f32_e32 v66, 0x3e0293ee, v95
	s_and_b64 vcc, s[10:11], vcc
	v_sub_f32_e32 v67, v141, v252
	v_add_u32_e32 v68, -9, v171
	v_cndmask_b32_e32 v172, v66, v219, vcc
	v_cmp_gt_i32_e32 vcc, v68, v134
	v_fmac_f32_e32 v67, 0x3e0293ee, v96
	s_and_b64 vcc, s[10:11], vcc
	v_add_u32_e32 v68, -8, v171
	v_cndmask_b32_e32 v170, v67, v219, vcc
	v_sub_f32_e32 v67, v141, v253
	v_cmp_gt_i32_e32 vcc, v68, v134
	v_fmac_f32_e32 v67, 0x3e0293ee, v97
	s_and_b64 vcc, s[10:11], vcc
	v_max3_f32 v66, v70, v181, v172
	v_cndmask_b32_e32 v171, v67, v219, vcc
	v_max3_f32 v66, v66, v170, v171
	ds_bpermute_b32 v67, v143, v66
	s_waitcnt lgkmcnt(0)
	v_max_f32_e32 v67, v67, v67
	v_max_f32_e32 v66, v66, v67
	v_add_f32_e32 v67, 0x41000000, v164
	v_cmp_gt_f32_e32 vcc, v66, v67
	s_cbranch_vccz .LBB0_477
	v_max_f32_e32 v66, v66, v66
	v_max_f32_e32 v67, v164, v164
	v_max_f32_e32 v67, v67, v66
	v_sub_f32_e32 v66, v164, v67
	v_exp_f32_e32 v66, v66
	v_mov_b32_e32 v164, v67
	v_pk_mul_f32 v[64:65], v[64:65], v[66:67] op_sel_hi:[1,0]
	v_pk_mul_f32 v[62:63], v[62:63], v[66:67] op_sel_hi:[1,0]
	v_pk_mul_f32 v[60:61], v[60:61], v[66:67] op_sel_hi:[1,0]
	v_pk_mul_f32 v[58:59], v[58:59], v[66:67] op_sel_hi:[1,0]
	v_pk_mul_f32 v[56:57], v[56:57], v[66:67] op_sel_hi:[1,0]
	v_pk_mul_f32 v[54:55], v[54:55], v[66:67] op_sel_hi:[1,0]
	v_pk_mul_f32 v[52:53], v[52:53], v[66:67] op_sel_hi:[1,0]
	v_pk_mul_f32 v[50:51], v[50:51], v[66:67] op_sel_hi:[1,0]
	v_pk_mul_f32 v[48:49], v[48:49], v[66:67] op_sel_hi:[1,0]
	v_pk_mul_f32 v[46:47], v[46:47], v[66:67] op_sel_hi:[1,0]
	v_pk_mul_f32 v[44:45], v[44:45], v[66:67] op_sel_hi:[1,0]
	v_pk_mul_f32 v[42:43], v[42:43], v[66:67] op_sel_hi:[1,0]
	v_pk_mul_f32 v[40:41], v[40:41], v[66:67] op_sel_hi:[1,0]
	v_pk_mul_f32 v[38:39], v[38:39], v[66:67] op_sel_hi:[1,0]
	v_pk_mul_f32 v[36:37], v[36:37], v[66:67] op_sel_hi:[1,0]
	v_pk_mul_f32 v[34:35], v[34:35], v[66:67] op_sel_hi:[1,0]
	v_pk_mul_f32 v[32:33], v[32:33], v[66:67] op_sel_hi:[1,0]
	v_pk_mul_f32 v[30:31], v[30:31], v[66:67] op_sel_hi:[1,0]
	v_pk_mul_f32 v[28:29], v[28:29], v[66:67] op_sel_hi:[1,0]
	v_pk_mul_f32 v[26:27], v[26:27], v[66:67] op_sel_hi:[1,0]
	v_pk_mul_f32 v[24:25], v[24:25], v[66:67] op_sel_hi:[1,0]
	v_pk_mul_f32 v[22:23], v[22:23], v[66:67] op_sel_hi:[1,0]
	v_pk_mul_f32 v[20:21], v[20:21], v[66:67] op_sel_hi:[1,0]
	v_pk_mul_f32 v[18:19], v[18:19], v[66:67] op_sel_hi:[1,0]
	v_pk_mul_f32 v[16:17], v[16:17], v[66:67] op_sel_hi:[1,0]
	v_pk_mul_f32 v[14:15], v[14:15], v[66:67] op_sel_hi:[1,0]
	v_pk_mul_f32 v[12:13], v[12:13], v[66:67] op_sel_hi:[1,0]
	v_pk_mul_f32 v[10:11], v[10:11], v[66:67] op_sel_hi:[1,0]
	v_pk_mul_f32 v[8:9], v[8:9], v[66:67] op_sel_hi:[1,0]
	v_pk_mul_f32 v[6:7], v[6:7], v[66:67] op_sel_hi:[1,0]
	v_pk_mul_f32 v[4:5], v[4:5], v[66:67] op_sel_hi:[1,0]
	v_pk_mul_f32 v[2:3], v[2:3], v[66:67] op_sel_hi:[1,0]
	v_mul_f32_e32 v161, v161, v66

; template <int MODE>
; DI void attn_item(const u16* Qp, int ldq, const u16* Kp, int ldk, const u16* VTp, int ldv, u16* Op, int ldo,
;                   int q0, int nkt, const float* Fc, const unsigned* BM, float kmaxn, char* smem) {
;     ...
;     l_run += ps;
;     asm volatile("s_waitcnt vmcnt(4)" ::: "memory");
;     if (MODE == 1 && tid < 16) *(f32x4*)(fct + ((kt + 1) & 3) * 64 + tid * 4) = rf;
.Lfox_join:
	s_waitcnt vmcnt(4)
	s_and_saveexec_b64 s[10:11], s[6:7]
	s_cbranch_execz .LBB0_479
	v_lshl_add_u32 v189, s14, 8, v155
	s_waitcnt vmcnt(0)
	ds_write_b128 v189, v[130:133]

; DI float shflx(float v, int m, int lane) { return __int_as_float(__builtin_amdgcn_ds_bpermute((lane ^ m) << 2, __float_as_int(v))); }
; template <int MODE>
; DI void attn_item(const u16* Qp, int ldq, const u16* Kp, int ldk, const u16* VTp, int ldv, u16* Op, int ldo,
;                   int q0, int nkt, const float* Fc, const unsigned* BM, float kmaxn, char* smem) {
;     ...
;     float mx = -1e30f;
;     if (MODE == 1) {
; #pragma unroll
;       for (int k2 = 0; k2 < 2; ++k2)
; #pragma unroll
;         for (int j = 0; j < 4; ++j) {
;           const int kl = 32 * k2 + 16 * (j >> 1) + 8 * h + 4 * (j & 1);
;           const f32x4 f4 = *(const f32x4*)(sF + kl);
; #pragma unroll
;           for (int i = 0; i < 4; ++i) {
;             float x = sc[k2][j * 4 + i] * c1 + (fcq - f4[i]);
;             if (diag && (ts + kl + i > q)) x = -1e30f;
;             sc[k2][j * 4 + i] = x;
;             mx = fmaxf(mx, x);
;           }
;         }
;     } else {
; #pragma unroll
;       for (int k2 = 0; k2 < 2; ++k2)
; #pragma unroll
;         for (int e = 0; e < 16; ++e) mx = fmaxf(mx, sc[k2][e]);
;       mx *= c1;
;     }
;     mx = fmaxf(mx, shflx(mx, 32, lane));
;     if (__any(mx > m_run + 8.f)) {
;       const float m_new = fmaxf(m_run, mx);
;       const float alpha = __builtin_amdgcn_exp2f(m_run - m_new);
;       m_run = m_new; l_run *= alpha;
; #pragma unroll
;       for (int i = 0; i < 4; ++i)
; #pragma unroll
;         for (int e = 0; e < 16; ++e) o[i][e] *= alpha;
;     }
.Lfox_fast:
	s_mov_b32 s14, 0xf149f2ca
	s_waitcnt lgkmcnt(0)
	v_sub_f32_e32 v166, v141, v166
	v_fmac_f32_e32 v166, 0x3e0293ee, v66
	v_sub_f32_e32 v66, v141, v167
	v_mov_b32_e32 v185, v166
	v_fmac_f32_e32 v66, 0x3e0293ee, v67
	v_sub_f32_e32 v67, v141, v168
	v_fmac_f32_e32 v67, 0x3e0293ee, v68
	v_subrev_u32_e32 v68, 61, v171
	v_mov_b32_e32 v191, v66
	v_subrev_u32_e32 v68, 60, v171
	v_mov_b32_e32 v192, v67
	v_sub_f32_e32 v67, v141, v169
	v_fmac_f32_e32 v67, 0x3e0293ee, v69
	v_mov_b32_e32 v193, v67
	v_subrev_u32_e32 v67, 59, v171
	v_sub_f32_e32 v68, v141, v172
	v_fmac_f32_e32 v68, 0x3e0293ee, v70
	v_mov_b32_e32 v198, v68
	v_sub_f32_e32 v68, v141, v173
	v_fmac_f32_e32 v68, 0x3e0293ee, v71
	v_mov_b32_e32 v197, v68
	v_subrev_u32_e32 v68, 57, v171
	v_sub_f32_e32 v67, v141, v174
	v_fmac_f32_e32 v67, 0x3e0293ee, v72
	v_subrev_u32_e32 v68, 56, v171
	v_max3_f32 v66, v185, s14, v191
	v_mov_b32_e32 v195, v67
	v_sub_f32_e32 v67, v141, v175
	v_max3_f32 v66, v66, v192, v193
	v_fmac_f32_e32 v67, 0x3e0293ee, v73
	v_max3_f32 v66, v66, v198, v197
	v_mov_b32_e32 v196, v67
	v_max3_f32 v70, v66, v195, v196
	v_subrev_u32_e32 v71, 47, v171
	s_waitcnt lgkmcnt(0)
	v_sub_f32_e32 v66, v141, v212
	v_fmac_f32_e32 v66, 0x3e0293ee, v74
	v_mov_b32_e32 v184, v66
	v_sub_f32_e32 v66, v141, v213
	v_fmac_f32_e32 v66, 0x3e0293ee, v75
	v_sub_f32_e32 v67, v141, v214
	v_subrev_u32_e32 v68, 45, v171
	v_mov_b32_e32 v183, v66
	v_fmac_f32_e32 v67, 0x3e0293ee, v76
	v_subrev_u32_e32 v68, 44, v171
	v_mov_b32_e32 v182, v67
	v_sub_f32_e32 v67, v141, v215
	v_fmac_f32_e32 v67, 0x3e0293ee, v77
	v_max3_f32 v66, v70, v184, v183
	v_mov_b32_e32 v179, v67
	v_max3_f32 v70, v66, v182, v179
	v_subrev_u32_e32 v71, 43, v171
	s_waitcnt lgkmcnt(0)
	v_sub_f32_e32 v66, v141, v234
	v_fmac_f32_e32 v66, 0x3e0293ee, v78
	v_mov_b32_e32 v194, v66
	v_sub_f32_e32 v66, v141, v235
	v_fmac_f32_e32 v66, 0x3e0293ee, v79
	v_sub_f32_e32 v67, v141, v236
	v_subrev_u32_e32 v68, 41, v171
	v_mov_b32_e32 v188, v66
	v_fmac_f32_e32 v67, 0x3e0293ee, v80
	v_subrev_u32_e32 v68, 40, v171
	v_mov_b32_e32 v186, v67
	v_sub_f32_e32 v67, v141, v237
	v_fmac_f32_e32 v67, 0x3e0293ee, v81
	v_max3_f32 v66, v70, v194, v188
	v_mov_b32_e32 v187, v67
	v_max3_f32 v70, v66, v186, v187
	v_subrev_u32_e32 v71, 31, v171
	s_waitcnt lgkmcnt(0)
	v_sub_f32_e32 v66, v141, v238
	v_fmac_f32_e32 v66, 0x3e0293ee, v82
	v_mov_b32_e32 v176, v66
	v_sub_f32_e32 v66, v141, v239
	v_fmac_f32_e32 v66, 0x3e0293ee, v83
	v_sub_f32_e32 v67, v141, v240
	v_subrev_u32_e32 v68, 29, v171
	v_mov_b32_e32 v175, v66
	v_fmac_f32_e32 v67, 0x3e0293ee, v84
	v_subrev_u32_e32 v68, 28, v171
	v_mov_b32_e32 v174, v67
	v_sub_f32_e32 v67, v141, v241
	v_fmac_f32_e32 v67, 0x3e0293ee, v85
	v_max3_f32 v66, v70, v176, v175
	v_mov_b32_e32 v173, v67
	v_max3_f32 v70, v66, v174, v173
	v_subrev_u32_e32 v71, 27, v171
	s_waitcnt lgkmcnt(0)
	v_sub_f32_e32 v66, v141, v242
	v_fmac_f32_e32 v66, 0x3e0293ee, v86
	v_mov_b32_e32 v190, v66
	v_sub_f32_e32 v66, v141, v243
	v_fmac_f32_e32 v66, 0x3e0293ee, v87
	v_sub_f32_e32 v67, v141, v244
	v_subrev_u32_e32 v68, 25, v171
	v_mov_b32_e32 v180, v66
	v_fmac_f32_e32 v67, 0x3e0293ee, v88
	v_subrev_u32_e32 v68, 24, v171
	v_mov_b32_e32 v177, v67
	v_sub_f32_e32 v67, v141, v245
	v_fmac_f32_e32 v67, 0x3e0293ee, v89
	v_max3_f32 v66, v70, v190, v180
	v_mov_b32_e32 v178, v67
	v_max3_f32 v70, v66, v177, v178
	v_add_u32_e32 v71, -15, v171
	s_waitcnt lgkmcnt(0)
	v_sub_f32_e32 v66, v141, v246
	v_fmac_f32_e32 v66, 0x3e0293ee, v90
	v_mov_b32_e32 v169, v66
	v_sub_f32_e32 v66, v141, v247
	v_fmac_f32_e32 v66, 0x3e0293ee, v91
	v_sub_f32_e32 v67, v141, v248
	v_add_u32_e32 v68, -13, v171
	v_mov_b32_e32 v168, v66
	v_fmac_f32_e32 v67, 0x3e0293ee, v92
	v_add_u32_e32 v68, -12, v171
	v_mov_b32_e32 v167, v67
	v_sub_f32_e32 v67, v141, v249
	v_fmac_f32_e32 v67, 0x3e0293ee, v93
	v_max3_f32 v66, v70, v169, v168
	v_mov_b32_e32 v166, v67
	v_max3_f32 v70, v66, v167, v166
	v_add_u32_e32 v71, -11, v171
	s_waitcnt lgkmcnt(0)
	v_sub_f32_e32 v66, v141, v250
	v_fmac_f32_e32 v66, 0x3e0293ee, v94
	v_mov_b32_e32 v181, v66
	v_sub_f32_e32 v66, v141, v251
	v_fmac_f32_e32 v66, 0x3e0293ee, v95
	v_sub_f32_e32 v67, v141, v252
	v_add_u32_e32 v68, -9, v171
	v_mov_b32_e32 v172, v66
	v_fmac_f32_e32 v67, 0x3e0293ee, v96
	v_add_u32_e32 v68, -8, v171
	v_mov_b32_e32 v170, v67
	v_sub_f32_e32 v67, v141, v253
	v_fmac_f32_e32 v67, 0x3e0293ee, v97
	v_max3_f32 v66, v70, v181, v172
	v_mov_b32_e32 v171, v67
	v_max3_f32 v66, v66, v170, v171
	ds_bpermute_b32 v67, v143, v66
	s_waitcnt lgkmcnt(0)
	v_max_f32_e32 v67, v67, v67
	v_max_f32_e32 v66, v66, v67
	v_add_f32_e32 v67, 0x41000000, v164
	v_cmp_gt_f32_e32 vcc, v66, v67
	s_cbranch_vccz .Lfox_f477
	v_max_f32_e32 v66, v66, v66
	v_max_f32_e32 v67, v164, v164
	v_max_f32_e32 v67, v67, v66
	v_sub_f32_e32 v66, v164, v67
	v_exp_f32_e32 v66, v66
	v_mov_b32_e32 v164, v67
	v_pk_mul_f32 v[64:65], v[64:65], v[66:67] op_sel_hi:[1,0]
	v_pk_mul_f32 v[62:63], v[62:63], v[66:67] op_sel_hi:[1,0]
	v_pk_mul_f32 v[60:61], v[60:61], v[66:67] op_sel_hi:[1,0]
	v_pk_mul_f32 v[58:59], v[58:59], v[66:67] op_sel_hi:[1,0]
	v_pk_mul_f32 v[56:57], v[56:57], v[66:67] op_sel_hi:[1,0]
	v_pk_mul_f32 v[54:55], v[54:55], v[66:67] op_sel_hi:[1,0]
	v_pk_mul_f32 v[52:53], v[52:53], v[66:67] op_sel_hi:[1,0]
	v_pk_mul_f32 v[50:51], v[50:51], v[66:67] op_sel_hi:[1,0]
	v_pk_mul_f32 v[48:49], v[48:49], v[66:67] op_sel_hi:[1,0]
	v_pk_mul_f32 v[46:47], v[46:47], v[66:67] op_sel_hi:[1,0]
	v_pk_mul_f32 v[44:45], v[44:45], v[66:67] op_sel_hi:[1,0]
	v_pk_mul_f32 v[42:43], v[42:43], v[66:67] op_sel_hi:[1,0]
	v_pk_mul_f32 v[40:41], v[40:41], v[66:67] op_sel_hi:[1,0]
	v_pk_mul_f32 v[38:39], v[38:39], v[66:67] op_sel_hi:[1,0]
	v_pk_mul_f32 v[36:37], v[36:37], v[66:67] op_sel_hi:[1,0]
	v_pk_mul_f32 v[34:35], v[34:35], v[66:67] op_sel_hi:[1,0]
	v_pk_mul_f32 v[32:33], v[32:33], v[66:67] op_sel_hi:[1,0]
	v_pk_mul_f32 v[30:31], v[30:31], v[66:67] op_sel_hi:[1,0]
	v_pk_mul_f32 v[28:29], v[28:29], v[66:67] op_sel_hi:[1,0]
	v_pk_mul_f32 v[26:27], v[26:27], v[66:67] op_sel_hi:[1,0]
	v_pk_mul_f32 v[24:25], v[24:25], v[66:67] op_sel_hi:[1,0]
	v_pk_mul_f32 v[22:23], v[22:23], v[66:67] op_sel_hi:[1,0]
	v_pk_mul_f32 v[20:21], v[20:21], v[66:67] op_sel_hi:[1,0]
	v_pk_mul_f32 v[18:19], v[18:19], v[66:67] op_sel_hi:[1,0]
	v_pk_mul_f32 v[16:17], v[16:17], v[66:67] op_sel_hi:[1,0]
	v_pk_mul_f32 v[14:15], v[14:15], v[66:67] op_sel_hi:[1,0]
	v_pk_mul_f32 v[12:13], v[12:13], v[66:67] op_sel_hi:[1,0]
	v_pk_mul_f32 v[10:11], v[10:11], v[66:67] op_sel_hi:[1,0]
	v_pk_mul_f32 v[8:9], v[8:9], v[66:67] op_sel_hi:[1,0]
	v_pk_mul_f32 v[6:7], v[6:7], v[66:67] op_sel_hi:[1,0]
	v_pk_mul_f32 v[4:5], v[4:5], v[66:67] op_sel_hi:[1,0]
	v_pk_mul_f32 v[2:3], v[2:3], v[66:67] op_sel_hi:[1,0]
	v_mul_f32_e32 v161, v161, v66
; #define MFMA(a, b, c) __builtin_amdgcn_mfma_f32_32x32x16_bf16((a), (b), (c), 0, 0, 0)
; template <int MODE>
; DI void attn_item(const u16* Qp, int ldq, const u16* Kp, int ldk, const u16* VTp, int ldv, u16* Op, int ldo,
;                   int q0, int nkt, const float* Fc, const unsigned* BM, float kmaxn, char* smem) {
;     ...
;     f32x16 sn[2];
;     float ps = 0.f;
; #pragma unroll
;     for (int g4 = 0; g4 < 4; ++g4) {
;       const int k2 = g4 >> 1, s2 = g4 & 1;
;       const f32x16 zero16 = {0.f, 0.f, 0.f, 0.f, 0.f, 0.f, 0.f, 0.f, 0.f, 0.f, 0.f, 0.f, 0.f, 0.f, 0.f, 0.f};
; #pragma unroll
;       for (int st = s2 * 4; st < s2 * 4 + 4; ++st) {
;         bf16x8 a = *(const bf16x8*)(sKn + kro + k2 * 8192 + (((st * 2 + h) ^ ksw) << 4));
;         sn[k2] = (st == 0) ? MFMA(a, qf[st], zero16) : MFMA(a, qf[st], sn[k2]);
;       }
;       const unsigned wbits = k2 ? bw.y : bw.x;
;       float pv8[8];
; #pragma unroll
;       for (int e8 = 0; e8 < 8; ++e8) {
;         const int e = 8 * s2 + e8;
;         float pv;
;         if (MODE == 1) {
;           const float x = sc[k2][e];
;           pv = __builtin_amdgcn_exp2f(x - m_run);
;           if (diag) pv = (x <= -1e29f) ? 0.f : pv;
;         } else {
;           pv = __builtin_amdgcn_exp2f(sc[k2][e] * c1 - m_run);
;           if (MODE == 2) {
;             const int kb = 16 * ((e >> 2) >> 1) + 8 * h + 4 * ((e >> 2) & 1) + (e & 3);
;             const int msk = __builtin_amdgcn_sbfe(wbits, kb, 1);
;             pv = __int_as_float(__float_as_int(pv) & msk);
;           }
;         }
;         pv8[e8] = pv; ps += pv;
;       }
;       u32x4 u;
;       u[0] = pk2(pv8[0], pv8[1]); u[1] = pk2(pv8[2], pv8[3]); u[2] = pk2(pv8[4], pv8[5]); u[3] = pk2(pv8[6], pv8[7]);
;       const bf16x8 pfg = __builtin_bit_cast(bf16x8, u);
; #pragma unroll
;       for (int dt = 0; dt < 4; ++dt) {
;         bf16x8 a = *(const bf16x8*)(sV + vro + dt * 4096 + (((4 * k2 + 2 * s2 + h) ^ vsw) << 4));
;         o[dt] = MFMA(a, pfg, o[dt]);
;       }
;       __builtin_amdgcn_sched_barrier(0);
;     }
.Lfox_f477:
	s_and_b32 s14, s18, 3
	v_lshl_add_u32 v83, s14, 15, v145
	v_add_u32_e32 v82, v83, v146
	ds_read_b128 v[66:69], v82
	v_lshl_add_u32 v189, s15, 15, v163
	v_add_u32_e32 v202, v83, v147
	ds_read_b128 v[84:87], v202
	v_add_u32_e32 v92, v189, v157
	ds_read_b128 v[88:91], v92 offset:16384
	v_add_u32_e32 v200, v83, v148
	v_add_u32_e32 v199, v83, v149
	s_waitcnt lgkmcnt(0)
	v_mfma_f32_32x32x16_bf16 v[66:81], v[66:69], v[98:101], 0
	v_mfma_f32_32x32x16_bf16 v[66:81], v[84:87], v[102:105], v[66:81]
	ds_read_b128 v[84:87], v200
	s_waitcnt lgkmcnt(0)
	v_mfma_f32_32x32x16_bf16 v[66:81], v[84:87], v[106:109], v[66:81]
	ds_read_b128 v[84:87], v199
	s_waitcnt lgkmcnt(0)
	v_mfma_f32_32x32x16_bf16 v[66:81], v[84:87], v[110:113], v[66:81]
	v_sub_f32_e32 v84, v185, v164
	v_exp_f32_e32 v185, v84
	s_nop 0
	v_sub_f32_e32 v84, v191, v164
	v_exp_f32_e32 v191, v84
	v_sub_f32_e32 v84, v192, v164
	v_exp_f32_e32 v192, v84
	v_sub_f32_e32 v84, v193, v164
	v_exp_f32_e32 v193, v84
	v_sub_f32_e32 v84, v198, v164
	v_exp_f32_e32 v198, v84
	v_cvt_pk_bf16_f32 v85, v192, v193
	v_sub_f32_e32 v84, v197, v164
	v_exp_f32_e32 v197, v84
	v_sub_f32_e32 v84, v195, v164
	v_exp_f32_e32 v195, v84
	v_cvt_pk_bf16_f32 v86, v198, v197
	v_sub_f32_e32 v84, v196, v164
	v_exp_f32_e32 v196, v84
	v_cvt_pk_bf16_f32 v84, v185, v191
	v_cvt_pk_bf16_f32 v87, v195, v196
	s_nop 1
	v_mfma_f32_32x32x16_bf16 v[50:65], v[88:91], v[84:87], v[50:65]
	ds_read_b128 v[88:91], v92 offset:20480
	s_waitcnt lgkmcnt(0)
	v_mfma_f32_32x32x16_bf16 v[34:49], v[88:91], v[84:87], v[34:49]
	ds_read_b128 v[88:91], v92 offset:24576
	s_waitcnt lgkmcnt(0)
	v_mfma_f32_32x32x16_bf16 v[18:33], v[88:91], v[84:87], v[18:33]
	ds_read_b128 v[88:91], v92 offset:28672
	s_waitcnt lgkmcnt(0)
	v_mfma_f32_32x32x16_bf16 v[2:17], v[88:91], v[84:87], v[2:17]
	v_add_u32_e32 v204, v83, v150
	v_add_u32_e32 v206, v83, v151
	v_add_u32_e32 v208, v83, v152
	v_add_u32_e32 v210, v83, v153
	v_sub_f32_e32 v83, v184, v164
	v_exp_f32_e32 v184, v83
	v_sub_f32_e32 v83, v183, v164
	v_exp_f32_e32 v183, v83
	ds_read_b128 v[84:87], v204
	v_sub_f32_e32 v83, v182, v164
	v_exp_f32_e32 v182, v83
	v_sub_f32_e32 v83, v179, v164
	v_exp_f32_e32 v179, v83
	v_sub_f32_e32 v83, v194, v164
	v_exp_f32_e32 v194, v83
	v_sub_f32_e32 v83, v188, v164
	v_exp_f32_e32 v188, v83
	v_sub_f32_e32 v83, v186, v164
	v_exp_f32_e32 v186, v83
	v_sub_f32_e32 v83, v187, v164
	v_exp_f32_e32 v187, v83
	v_add_u32_e32 v83, v189, v158
	ds_read_b128 v[88:91], v83 offset:16384
	s_waitcnt lgkmcnt(0)
	v_mfma_f32_32x32x16_bf16 v[66:81], v[84:87], v[114:117], v[66:81]
	ds_read_b128 v[84:87], v206
	s_waitcnt lgkmcnt(0)
	v_mfma_f32_32x32x16_bf16 v[66:81], v[84:87], v[118:121], v[66:81]
	ds_read_b128 v[84:87], v208
	s_waitcnt lgkmcnt(0)
	v_mfma_f32_32x32x16_bf16 v[66:81], v[84:87], v[122:125], v[66:81]
	ds_read_b128 v[84:87], v210
	s_waitcnt lgkmcnt(0)
	v_mfma_f32_32x32x16_bf16 v[66:81], v[84:87], v[126:129], v[66:81]
	v_cvt_pk_bf16_f32 v84, v184, v183
	v_cvt_pk_bf16_f32 v85, v182, v179
	v_cvt_pk_bf16_f32 v86, v194, v188
	v_cvt_pk_bf16_f32 v87, v186, v187
	s_nop 1
	v_mfma_f32_32x32x16_bf16 v[50:65], v[88:91], v[84:87], v[50:65]
	ds_read_b128 v[88:91], v83 offset:20480
	s_waitcnt lgkmcnt(0)
	v_mfma_f32_32x32x16_bf16 v[34:49], v[88:91], v[84:87], v[34:49]
	ds_read_b128 v[88:91], v83 offset:24576
	s_waitcnt lgkmcnt(0)
	v_mfma_f32_32x32x16_bf16 v[18:33], v[88:91], v[84:87], v[18:33]
	ds_read_b128 v[88:91], v83 offset:28672
	s_waitcnt lgkmcnt(0)
	v_mfma_f32_32x32x16_bf16 v[2:17], v[88:91], v[84:87], v[2:17]
	ds_read_b128 v[82:85], v82 offset:8192
	ds_read_b128 v[226:229], v202 offset:8192
	s_waitcnt lgkmcnt(0)
	v_mfma_f32_32x32x16_bf16 v[82:97], v[82:85], v[98:101], 0
	v_mfma_f32_32x32x16_bf16 v[82:97], v[226:229], v[102:105], v[82:97]
	ds_read_b128 v[226:229], v200 offset:8192
	s_waitcnt lgkmcnt(0)
	v_mfma_f32_32x32x16_bf16 v[82:97], v[226:229], v[106:109], v[82:97]
	ds_read_b128 v[226:229], v199 offset:8192
	v_sub_f32_e32 v199, v176, v164
	v_exp_f32_e32 v176, v199
	s_nop 0
	v_sub_f32_e32 v199, v175, v164
	v_exp_f32_e32 v175, v199
	s_waitcnt lgkmcnt(0)
	v_mfma_f32_32x32x16_bf16 v[82:97], v[226:229], v[110:113], v[82:97]
	v_sub_f32_e32 v199, v174, v164
	v_exp_f32_e32 v174, v199
	v_cvt_pk_bf16_f32 v226, v176, v175
	v_sub_f32_e32 v199, v173, v164
	v_exp_f32_e32 v173, v199
	v_sub_f32_e32 v199, v190, v164
	v_exp_f32_e32 v190, v199
	v_cvt_pk_bf16_f32 v227, v174, v173
	v_sub_f32_e32 v199, v180, v164
	v_exp_f32_e32 v180, v199
	v_sub_f32_e32 v199, v177, v164
	v_exp_f32_e32 v177, v199
	v_cvt_pk_bf16_f32 v228, v190, v180
	v_sub_f32_e32 v199, v178, v164
	v_exp_f32_e32 v178, v199
	v_add_u32_e32 v199, v189, v159
	ds_read_b128 v[230:233], v199 offset:16384
	v_cvt_pk_bf16_f32 v229, v177, v178
	s_waitcnt lgkmcnt(0)
	s_nop 0
	v_mfma_f32_32x32x16_bf16 v[50:65], v[230:233], v[226:229], v[50:65]
	ds_read_b128 v[230:233], v199 offset:20480
	s_waitcnt lgkmcnt(0)
	v_mfma_f32_32x32x16_bf16 v[34:49], v[230:233], v[226:229], v[34:49]
	ds_read_b128 v[230:233], v199 offset:24576
	s_waitcnt lgkmcnt(0)
	v_mfma_f32_32x32x16_bf16 v[18:33], v[230:233], v[226:229], v[18:33]
	ds_read_b128 v[230:233], v199 offset:28672
	s_waitcnt lgkmcnt(0)
	v_mfma_f32_32x32x16_bf16 v[2:17], v[230:233], v[226:229], v[2:17]
	v_sub_f32_e32 v199, v169, v164
	v_exp_f32_e32 v169, v199
	ds_read_b128 v[202:205], v204 offset:8192
	v_sub_f32_e32 v199, v168, v164
	v_exp_f32_e32 v168, v199
	v_sub_f32_e32 v199, v167, v164
	v_exp_f32_e32 v167, v199
	s_waitcnt lgkmcnt(0)
	v_mfma_f32_32x32x16_bf16 v[82:97], v[202:205], v[114:117], v[82:97]
	ds_read_b128 v[202:205], v206 offset:8192
	v_sub_f32_e32 v199, v166, v164
	v_exp_f32_e32 v166, v199
	s_waitcnt lgkmcnt(0)
	v_mfma_f32_32x32x16_bf16 v[82:97], v[202:205], v[118:121], v[82:97]
	v_sub_f32_e32 v199, v181, v164
	v_exp_f32_e32 v181, v199
	ds_read_b128 v[202:205], v208 offset:8192
	v_sub_f32_e32 v199, v172, v164
	v_exp_f32_e32 v172, v199
	s_waitcnt lgkmcnt(0)
	v_mfma_f32_32x32x16_bf16 v[82:97], v[202:205], v[122:125], v[82:97]
	v_sub_f32_e32 v199, v170, v164
	v_exp_f32_e32 v170, v199
	ds_read_b128 v[202:205], v210 offset:8192
	v_add_u32_e32 v189, v189, v160
	ds_read_b128 v[206:209], v189 offset:16384
	v_sub_f32_e32 v199, v171, v164
	v_exp_f32_e32 v171, v199
	s_waitcnt lgkmcnt(0)
	v_mfma_f32_32x32x16_bf16 v[82:97], v[202:205], v[126:129], v[82:97]
	v_cvt_pk_bf16_f32 v202, v169, v168
	v_cvt_pk_bf16_f32 v203, v167, v166
	v_cvt_pk_bf16_f32 v204, v181, v172
	v_cvt_pk_bf16_f32 v205, v170, v171
	s_nop 1
	v_mfma_f32_32x32x16_bf16 v[50:65], v[206:209], v[202:205], v[50:65]
	ds_read_b128 v[206:209], v189 offset:20480
	s_waitcnt lgkmcnt(0)
	v_mfma_f32_32x32x16_bf16 v[34:49], v[206:209], v[202:205], v[34:49]
	ds_read_b128 v[206:209], v189 offset:24576
	s_waitcnt lgkmcnt(0)
	v_mfma_f32_32x32x16_bf16 v[18:33], v[206:209], v[202:205], v[18:33]
	ds_read_b128 v[206:209], v189 offset:28672
	s_waitcnt lgkmcnt(0)
	v_mfma_f32_32x32x16_bf16 v[2:17], v[206:209], v[202:205], v[2:17]
	s_branch .Lfox_join
